# combined lean chunk code: two-address LDS ops, single Q/K load batch for the Q K^T tiles, no chunk-entry barrier
# speedup vs baseline: 1.0057x; 1.0010x over previous
; __device__ __forceinline__ void dn_task(const Params& p, int l, int task, char* smem) {
;     ...
;     {
;       const int did = tid >> 2, pp = did >> 2, wh = did & 3, part = tid & 3;
;       const float* xr = (wh == 0) ? (ks + (2 * pp + 1) * 68) : (wh == 1) ? (qs + (2 * pp) * 68) : (qs + (2 * pp + 1) * 68);
;       const float* yr = (wh == 3) ? (ks + (2 * pp + 1) * 68) : (ks + (2 * pp) * 68);
;       float sdot = 0.f;
; #pragma unroll
;       for (int i = 0; i < 16; ++i) sdot += xr[part * 16 + i] * yr[part * 16 + i];
;       sdot = quad_sum(sdot);
;       if (part == 0) dots[did] = sdot;
;     }
.LBB0_207:
	v_and_b32_e32 v221, 63, v172
	v_and_b32_e32 v222, 15, v221
	v_lshrrev_b32_e32 v223, 4, v221
	v_mul_u32_u24_e32 v224, 0x110, v222
	v_lshl_add_u32 v224, v223, 6, v224
	v_mul_u32_u24_e32 v225, 0x240, v223
	v_lshl_add_u32 v225, v222, 2, v225
	v_readfirstlane_b32 s60, v172
	s_nop 3
	s_lshr_b32 s60, s60, 6
	v_lshrrev_b32_e32 v244, 3, v172
	v_lshlrev_b32_e32 v244, 2, v244
	v_sub_u32_e32 v248, v167, v244
	s_and_b32 s61, s60, 1
	s_lshl_b32 s61, s61, 6
	v_mul_u32_u24_e32 v244, 0x840, v223
	v_lshl_add_u32 v244, v222, 2, v244
	s_add_i32 s61, s61, 0x11600
	v_add_u32_e32 v244, s61, v244
	v_add_u32_e32 v245, 0x420, v244
	ds_read2_b32 v[10:11], v244 offset0:0 offset1:33
	ds_read2_b32 v[12:13], v244 offset0:66 offset1:99
	ds_read2_b32 v[14:15], v244 offset0:132 offset1:165
	ds_read2_b32 v[16:17], v244 offset0:198 offset1:231
	ds_read2_b32 v[18:19], v245 offset0:0 offset1:33
	ds_read2_b32 v[20:21], v245 offset0:66 offset1:99
	ds_read2_b32 v[22:23], v245 offset0:132 offset1:165
	ds_read2_b32 v[24:25], v245 offset0:198 offset1:231
	s_lshr_b32 s61, s60, 1
	s_mul_i32 s70, s61, 0x1100
	v_add_u32_e32 v246, s70, v224
	ds_read_b128 v[66:69], v246 offset:8704
	ds_read_b128 v[70:73], v246 offset:8720
	ds_read_b128 v[74:77], v246 offset:8736
	ds_read_b128 v[78:81], v246 offset:8752
	s_cmp_eq_u32 s60, 3
	s_cbranch_scc1 .Ldc_w3
	s_cmp_eq_u32 s60, 1
	s_cbranch_scc1 .Ldc_k1
	s_waitcnt lgkmcnt(0)
	v_mfma_f32_16x16x4_f32 v[62:65], v66, v10, 0
	v_mfma_f32_16x16x4_f32 v[58:61], v66, v66, 0
	v_mfma_f32_16x16x4_f32 v[62:65], v67, v11, v[62:65]
	v_mfma_f32_16x16x4_f32 v[58:61], v67, v67, v[58:61]
	v_mfma_f32_16x16x4_f32 v[62:65], v68, v12, v[62:65]
	v_mfma_f32_16x16x4_f32 v[58:61], v68, v68, v[58:61]
	v_mfma_f32_16x16x4_f32 v[62:65], v69, v13, v[62:65]
	v_mfma_f32_16x16x4_f32 v[58:61], v69, v69, v[58:61]
	v_mfma_f32_16x16x4_f32 v[62:65], v70, v14, v[62:65]
	v_mfma_f32_16x16x4_f32 v[58:61], v70, v70, v[58:61]
	v_mfma_f32_16x16x4_f32 v[62:65], v71, v15, v[62:65]
	v_mfma_f32_16x16x4_f32 v[58:61], v71, v71, v[58:61]
	v_mfma_f32_16x16x4_f32 v[62:65], v72, v16, v[62:65]
	v_mfma_f32_16x16x4_f32 v[58:61], v72, v72, v[58:61]
	v_mfma_f32_16x16x4_f32 v[62:65], v73, v17, v[62:65]
	v_mfma_f32_16x16x4_f32 v[58:61], v73, v73, v[58:61]
	v_mfma_f32_16x16x4_f32 v[62:65], v74, v18, v[62:65]
	v_mfma_f32_16x16x4_f32 v[58:61], v74, v74, v[58:61]
	v_mfma_f32_16x16x4_f32 v[62:65], v75, v19, v[62:65]
	v_mfma_f32_16x16x4_f32 v[58:61], v75, v75, v[58:61]
	v_mfma_f32_16x16x4_f32 v[62:65], v76, v20, v[62:65]
	v_mfma_f32_16x16x4_f32 v[58:61], v76, v76, v[58:61]
	v_mfma_f32_16x16x4_f32 v[62:65], v77, v21, v[62:65]
	v_mfma_f32_16x16x4_f32 v[58:61], v77, v77, v[58:61]
	v_mfma_f32_16x16x4_f32 v[62:65], v78, v22, v[62:65]
	v_mfma_f32_16x16x4_f32 v[58:61], v78, v78, v[58:61]
	v_mfma_f32_16x16x4_f32 v[62:65], v79, v23, v[62:65]
	v_mfma_f32_16x16x4_f32 v[58:61], v79, v79, v[58:61]
	v_mfma_f32_16x16x4_f32 v[62:65], v80, v24, v[62:65]
	v_mfma_f32_16x16x4_f32 v[58:61], v80, v80, v[58:61]
	v_mfma_f32_16x16x4_f32 v[62:65], v81, v25, v[62:65]
	v_mfma_f32_16x16x4_f32 v[58:61], v81, v81, v[58:61]
	s_branch .Ldc_b1
